# attention near loop hand-scheduled like the far loop (bias read from the LDS table into the accumulators)
# baseline (speedup 1.0000x reference)
; DI void attn_mfma_phase(PP P, int l, unsigned char* lds, int G, int cid) {
;     ...
;     for (int u = cid; u < 1024; u += G) {
;         const int w = u & 255, i = u >> 8, bh = (w & 7) * 4 + (w >> 6), r = (w >> 3) & 7, b = bh >> 3, h = bh & 7;
;         const int j = (i >> 1) * 16 + ((i & 1) ? 15 - r : r);
;         const int mychunk = 2 * j + (qg >> 1), qpos = j * 128 + qg * 32 + r32;
;         float mb = 0.f;
;         for (int k = 0; k < 32; ++k) mb = fmaxf(mb, fabsf(P->in[23][k * 8 + h]));
;         const float smax2 = (8.f * mq * mk + mb) * LOG2E;
;         __syncthreads();
;         if (tid < 192) tb2[tid] = P->in[23][t5_bucket(tid - 128) * 8 + h] * LOG2E - smax2;
.LBB0_209:
	s_lshl_b32 s4, s82, 2
	s_and_b32 s8, s4, 28
	s_bfe_u32 s4, s82, 0x20006
	s_or_b32 s7, s8, s4
	s_and_b32 s39, s7, 7
	s_and_b32 s4, s78, 0xff
	s_cmp_eq_u32 s4, 0
	s_cbranch_scc0 .Lattn_build_table
	s_cmp_lg_u32 s82, s79
	s_cbranch_scc1 .Lattn_keep_table
.Lattn_build_table:
	s_lshl_b32 s4, s39, 2
	v_mov_b32_e32 v24, s4
	s_lshl_b32 s4, s7, 2
	s_or_b32 s5, s4, 0x60
	v_mov_b32_e32 v25, s5
	s_or_b32 s5, s4, 0xe0
	v_mov_b32_e32 v26, s5
	s_or_b32 s5, s4, 0x160
	v_mov_b32_e32 v27, s5
	s_or_b32 s5, s4, 0x1e0
	v_mov_b32_e32 v28, s5
	s_or_b32 s5, s4, 0x260
	v_mov_b32_e32 v33, s5
	s_or_b32 s5, s4, 0x2e0
	v_mov_b32_e32 v34, s5
	s_or_b32 s5, s4, 0x360
	s_or_b32 s4, s4, 0x3e0
	s_waitcnt lgkmcnt(0)
	global_load_dword v0, v24, s[14:15]
	global_load_dword v2, v24, s[14:15] offset:32
	global_load_dword v3, v24, s[14:15] offset:64
	global_load_dword v4, v24, s[14:15] offset:128
	global_load_dword v5, v24, s[14:15] offset:160
	global_load_dword v6, v24, s[14:15] offset:192
	global_load_dword v7, v24, s[14:15] offset:256
	global_load_dword v8, v24, s[14:15] offset:288
	global_load_dword v9, v24, s[14:15] offset:320
	global_load_dword v10, v24, s[14:15] offset:384
	global_load_dword v11, v24, s[14:15] offset:416
	global_load_dword v12, v24, s[14:15] offset:448
	global_load_dword v13, v24, s[14:15] offset:512
	global_load_dword v14, v24, s[14:15] offset:544
	global_load_dword v15, v24, s[14:15] offset:576
	global_load_dword v16, v24, s[14:15] offset:640
	v_mov_b32_e32 v35, s5
	global_load_dword v17, v24, s[14:15] offset:672
	global_load_dword v18, v24, s[14:15] offset:704
	global_load_dword v19, v24, s[14:15] offset:768
	global_load_dword v20, v24, s[14:15] offset:800
	global_load_dword v21, v24, s[14:15] offset:832
	global_load_dword v22, v24, s[14:15] offset:896
	global_load_dword v23, v24, s[14:15] offset:928
	s_nop 0
	global_load_dword v24, v24, s[14:15] offset:960
	v_mov_b32_e32 v36, s4
	global_load_dword v32, v25, s[14:15]
	global_load_dword v31, v26, s[14:15]
	global_load_dword v30, v27, s[14:15]
	global_load_dword v29, v28, s[14:15]
	s_nop 0
	global_load_dword v28, v33, s[14:15]
	global_load_dword v27, v34, s[14:15]
	global_load_dword v26, v35, s[14:15]
	global_load_dword v25, v36, s[14:15]
	s_barrier
	s_and_saveexec_b64 s[12:13], s[40:41]
	s_cbranch_execz .LBB0_211
	v_or_b32_e32 v34, s39, v221
	v_ashrrev_i32_e32 v35, 31, v34
	v_lshl_add_u64 v[34:35], v[34:35], 2, s[14:15]
	global_load_dword v34, v[34:35], off
	s_waitcnt vmcnt(31)
	v_max3_f32 v0, |v0|, 0, |v2|
	s_waitcnt vmcnt(8)
	v_max3_f32 v0, v0, |v3|, |v32|
	v_max3_f32 v0, v0, |v4|, |v5|
	s_waitcnt vmcnt(7)
	v_max3_f32 v0, v0, |v6|, |v31|
	v_max3_f32 v0, v0, |v7|, |v8|
	s_waitcnt vmcnt(6)
	v_max3_f32 v0, v0, |v9|, |v30|
	v_max3_f32 v0, v0, |v10|, |v11|
	s_waitcnt vmcnt(5)
	v_max3_f32 v0, v0, |v12|, |v29|
	v_max3_f32 v0, v0, |v13|, |v14|
	s_waitcnt vmcnt(4)
	v_max3_f32 v0, v0, |v15|, |v28|
	v_max3_f32 v0, v0, |v16|, |v17|
	s_waitcnt vmcnt(3)
	v_max3_f32 v0, v0, |v18|, |v27|
	v_max3_f32 v0, v0, |v19|, |v20|
	s_waitcnt vmcnt(2)
	v_max3_f32 v0, v0, |v21|, |v26|
	v_max3_f32 v0, v0, |v22|, |v23|
	s_waitcnt vmcnt(1)
	v_max3_f32 v0, v0, |v24|, |v25|
	v_add_f32_e32 v35, v204, v0
	s_waitcnt vmcnt(0)
	v_pk_mul_f32 v[2:3], v[34:35], s[30:31] op_sel_hi:[1,0]
	s_nop 0
	v_sub_f32_e32 v0, v2, v3
	ds_write_b32 v205, v0

; #define MFMA32(a, b, c) __builtin_amdgcn_mfma_f32_32x32x16_bf16((a), (b), (c), 0, 0, 0)
; #define AT_LOADK(t) do { AT_DMA(kg[0] + (size_t)(t) * 65536, ldsl + ((t) & 1) * AT_KS + dw); AT_DMA(kg[1] + (size_t)(t) * 65536, ldsl + ((t) & 1) * AT_KS + dw + 1024); } while (0)
; #define AT_LOADV(t) do { AT_DMA(vg[0] + (t) * 64, ldsl + AT_V0 + ((t) & 1) * AT_KS + dw); AT_DMA(vg[1] + (t) * 64, ldsl + AT_V0 + ((t) & 1) * AT_KS + dw + 1024); } while (0)
; template <bool NEAR>
; DI void attn_qk(f32x16& s0, f32x16& s1, ldsp_t kb, const int* kro, const bf16x8* qf, int dtile, const float* tb2, int hi, int qg, int r32) {
;     ...
;         const int base = dtile * 64 + 8 * hi - (qg & 1) * 32 - r32 + 128;
; #pragma unroll
;         for (int k = 0; k < 16; ++k) { const int i0 = base + (k & 7) + 16 * (k >> 3), i1 = i0 + 32; s0[k] = tb2[i0 < 0 ? 0 : i0]; s1[k] = tb2[i1 < 0 ? 0 : i1]; }
;     }
; #pragma unroll
;     for (int ks = 0; ks < 4; ++ks) { s0 = MFMA32(a[2 * ks], qf[ks], s0); s1 = MFMA32(a[2 * ks + 1], qf[ks], s1); }
; DI void attn_pv(f32x16& s0, f32x16& s1, ldsp_t vb, const int* vro, f32x16* o, float& lsum) {
; #pragma unroll
;     for (int k = 0; k < 16; ++k) { s0[k] = __builtin_amdgcn_exp2f(s0[k]); s1[k] = __builtin_amdgcn_exp2f(s1[k]); }
;     float ps = 0.f;
; #pragma unroll
;     for (int k = 0; k < 16; ++k) ps += s0[k] + s1[k];
;     lsum += ps;
;     bf16x8 pk[4]; pk[0] = pack8(s0, 0); pk[1] = pack8(s0, 1); pk[2] = pack8(s1, 0); pk[3] = pack8(s1, 1);
; #pragma unroll
;     for (int kk = 0; kk < 4; ++kk)
; #pragma unroll
;         for (int et = 0; et < 4; ++et) {
;             const bf16x8 a = *(const __attribute__((address_space(3))) bf16x8*)(vb + vro[kk] + et * 4096);
;             o[et] = MFMA32(a, pk[kk], o[et]);
;         }
; }
; DI void attn_mfma_phase(PP P, int l, unsigned char* lds, int G, int cid) {
;     ...
;         for (; kt < 2 * j; ++kt) {
;             AT_LOADK(kt + 2); AT_LOADV(kt + 1);
;             attn_qk<true>(sn0, sn1, ldsl + ((kt + 1) & 1) * AT_KS, kro, qf, kt + 1 - mychunk, tb2, hi, qg, r32);
;             attn_pv(sc0, sc1, ldsl + (kt & 1) * AT_KS, vro, o, lsum);
;             sc0 = sn0; sc1 = sn1;
;             __syncthreads();
;         }
.LBB0_216:
	s_lshl_b32 s6, s43, 7
	v_subrev_u32_e32 v0, s6, v228
	s_lshl_b32 s6, s42, 7
	s_and_b32 s6, s6, 0xfffff800
	s_mov_b32 s39, s21
	s_lshl_b32 s84, s38, 6
	v_subrev_u32_e32 v232, s6, v0
	s_lshl_b32 s42, s38, 14
	s_lshl_b64 s[6:7], s[38:39], 17
	s_add_u32 s4, s4, s6
	s_addc_u32 s6, 0, s7
	s_add_u32 s4, s4, s5
	s_addc_u32 s5, s6, 0
	v_lshl_add_u64 v[10:11], v[184:185], 0, s[4:5]
	v_lshl_add_u64 v[12:13], v[186:187], 0, s[4:5]
	s_mov_b32 s4, 0xc0
	v_exp_f32_e32 v14, v96
	v_exp_f32_e32 v15, v97
	v_exp_f32_e32 v168, v98
	v_exp_f32_e32 v169, v99
	v_exp_f32_e32 v198, v100
	v_exp_f32_e32 v199, v101
	v_exp_f32_e32 v238, v102
	v_exp_f32_e32 v239, v103
	v_cvt_pk_bf16_f32 v128, v14, v15
	v_cvt_pk_bf16_f32 v129, v168, v169
	v_add_f32_e32 v14, v14, v15
	v_add_f32_e32 v168, v168, v169
	v_cvt_pk_bf16_f32 v130, v198, v199
	v_cvt_pk_bf16_f32 v131, v238, v239
	v_add_f32_e32 v198, v198, v199
	v_add_f32_e32 v238, v238, v239
	v_add_f32_e32 v14, v14, v168
	v_add_f32_e32 v198, v198, v238
	v_add_f32_e32 v235, v14, v198
.LBB0_217:
	s_and_b32 s6, s42, 0xc000
	s_addk_i32 s42, 0x4000
	s_add_i32 s7, s6, s64
	s_add_i32 s20, s84, s4
	s_and_b32 s5, s42, 0xc000
	v_add_u32_e32 v248, s6, v222
	v_add_u32_e32 v249, s6, v223
	s_add_i32 s10, s42, 0x8000
	s_and_b32 s10, s10, 0xc000
	s_add_i32 s10, s10, s65
	ds_read_b128 v[2:5], v248 offset:32768
	ds_read_b128 v[6:9], v248 offset:36864
	ds_read_b128 v[136:139], v248 offset:40960
	ds_read_b128 v[140:143], v248 offset:45056
	ds_read_b128 v[240:243], v249 offset:32768
	s_lshl_b64 s[8:9], s[20:21], 1
	s_mov_b32 m0, s7
	v_lshl_add_u64 v[236:237], v[194:195], 0, s[8:9]
	global_load_lds_dwordx4 v[12:13], off
	s_add_i32 m0, s7, 0x400
	v_add_u32_e32 v252, s5, v171
	global_load_lds_dwordx4 v[10:11], off
	s_add_i32 m0, s10, 0x10000
	v_add_u32_e32 v253, s5, v200
	global_load_lds_dwordx4 v[236:237], off
	v_lshl_add_u64 v[236:237], v[196:197], 0, s[8:9]
	s_add_i32 m0, s10, 0x10400
	v_add_u32_e32 v233, s5, v201
	global_load_lds_dwordx4 v[236:237], off
	v_add_u32_e32 v234, s5, v202
	v_add_u32_e32 v250, s6, v224
	v_add_u32_e32 v251, s6, v225
	v_add_f32_e32 v189, v189, v235
	v_add_u32_e32 v0, s84, v232
	v_exp_f32_e32 v14, v104
	v_exp_f32_e32 v15, v105
	v_exp_f32_e32 v168, v106
	v_exp_f32_e32 v169, v107
	v_exp_f32_e32 v198, v108
	v_exp_f32_e32 v199, v109
	v_exp_f32_e32 v238, v110
	v_exp_f32_e32 v239, v111
	s_waitcnt lgkmcnt(4)
	v_mfma_f32_32x32x16_bf16 v[64:79], v[2:5], v[128:131], v[64:79]
	ds_read_b128 v[244:247], v249 offset:36864
	v_cvt_pk_bf16_f32 v132, v14, v15
	v_cvt_pk_bf16_f32 v133, v168, v169
	v_add_f32_e32 v14, v14, v15
	v_add_f32_e32 v168, v168, v169
	v_add_u32_e32 v112, 0xc0, v0
	v_max_i32_e32 v112, 0, v112
	v_lshl_add_u32 v112, v112, 2, s61
	ds_read_b32 v96, v112
	v_add_u32_e32 v113, 0xc1, v0
	v_max_i32_e32 v113, 0, v113
	v_lshl_add_u32 v113, v113, 2, s61
	ds_read_b32 v97, v113
	s_waitcnt lgkmcnt(6)
	v_mfma_f32_32x32x16_bf16 v[48:63], v[6:9], v[128:131], v[48:63]
	ds_read_b128 v[2:5], v249 offset:40960
	v_cvt_pk_bf16_f32 v134, v198, v199
	v_cvt_pk_bf16_f32 v135, v238, v239
	v_add_f32_e32 v198, v198, v199
	v_add_f32_e32 v238, v238, v239
	v_add_u32_e32 v114, 0xc2, v0
	v_max_i32_e32 v114, 0, v114
	v_lshl_add_u32 v114, v114, 2, s61
	ds_read_b32 v98, v114
	v_add_u32_e32 v115, 0xc3, v0
	v_max_i32_e32 v115, 0, v115
	v_lshl_add_u32 v115, v115, 2, s61
	ds_read_b32 v99, v115
	s_waitcnt lgkmcnt(8)
	v_mfma_f32_32x32x16_bf16 v[32:47], v[136:139], v[128:131], v[32:47]
	ds_read_b128 v[6:9], v249 offset:45056
	v_add_f32_e32 v14, v14, v168
	v_add_f32_e32 v198, v198, v238
	v_add_f32_e32 v14, v14, v198
	v_add_f32_e32 v189, v189, v14
	v_add_u32_e32 v116, 0xc4, v0
	v_max_i32_e32 v116, 0, v116
	v_lshl_add_u32 v116, v116, 2, s61
	ds_read_b32 v100, v116
	v_add_u32_e32 v117, 0xc5, v0
	v_max_i32_e32 v117, 0, v117
	v_lshl_add_u32 v117, v117, 2, s61
	ds_read_b32 v101, v117
	s_waitcnt lgkmcnt(10)
	v_mfma_f32_32x32x16_bf16 v[16:31], v[140:143], v[128:131], v[16:31]
	ds_read_b128 v[136:139], v252
	v_exp_f32_e32 v14, v80
	v_exp_f32_e32 v15, v81
	v_exp_f32_e32 v168, v82
	v_add_u32_e32 v118, 0xc6, v0
	v_max_i32_e32 v118, 0, v118
	v_lshl_add_u32 v118, v118, 2, s61
	ds_read_b32 v102, v118
	v_add_u32_e32 v119, 0xc7, v0
	v_max_i32_e32 v119, 0, v119
	v_lshl_add_u32 v119, v119, 2, s61
	ds_read_b32 v103, v119
	v_add_u32_e32 v120, 0xd0, v0
	v_max_i32_e32 v120, 0, v120
	v_lshl_add_u32 v120, v120, 2, s61
	ds_read_b32 v104, v120
	s_waitcnt lgkmcnt(13)
	v_mfma_f32_32x32x16_bf16 v[64:79], v[240:243], v[132:135], v[64:79]
	ds_read_b128 v[140:143], v253
	v_exp_f32_e32 v169, v83
	v_exp_f32_e32 v198, v84
	v_exp_f32_e32 v199, v85
	v_add_u32_e32 v121, 0xd1, v0
	v_max_i32_e32 v121, 0, v121
	v_lshl_add_u32 v121, v121, 2, s61
	ds_read_b32 v105, v121
	v_add_u32_e32 v122, 0xd2, v0
	v_max_i32_e32 v122, 0, v122
	v_lshl_add_u32 v122, v122, 2, s61
	ds_read_b32 v106, v122
	v_add_u32_e32 v123, 0xd3, v0
	v_max_i32_e32 v123, 0, v123
	v_lshl_add_u32 v123, v123, 2, s61
	ds_read_b32 v107, v123
	s_waitcnt lgkmcnt(15)
	v_mfma_f32_32x32x16_bf16 v[48:63], v[244:247], v[132:135], v[48:63]
	ds_read_b128 v[240:243], v233
	v_exp_f32_e32 v238, v86
	v_exp_f32_e32 v239, v87
	v_cvt_pk_bf16_f32 v128, v14, v15
	v_add_u32_e32 v124, 0xd4, v0
	v_max_i32_e32 v124, 0, v124
	v_lshl_add_u32 v124, v124, 2, s61
	ds_read_b32 v108, v124
	v_add_u32_e32 v125, 0xd5, v0
	v_max_i32_e32 v125, 0, v125
	v_lshl_add_u32 v125, v125, 2, s61
	ds_read_b32 v109, v125
	s_waitcnt lgkmcnt(15)
	v_mfma_f32_32x32x16_bf16 v[32:47], v[2:5], v[132:135], v[32:47]
	ds_read_b128 v[244:247], v234
	v_cvt_pk_bf16_f32 v129, v168, v169
	v_add_f32_e32 v14, v14, v15
	v_add_f32_e32 v168, v168, v169
	v_add_u32_e32 v126, 0xd6, v0
	v_max_i32_e32 v126, 0, v126
	v_lshl_add_u32 v126, v126, 2, s61
	ds_read_b32 v110, v126
	v_add_u32_e32 v127, 0xd7, v0
	v_max_i32_e32 v127, 0, v127
	v_lshl_add_u32 v127, v127, 2, s61
	ds_read_b32 v111, v127
	s_waitcnt lgkmcnt(15)
; #define MFMA32(a, b, c) __builtin_amdgcn_mfma_f32_32x32x16_bf16((a), (b), (c), 0, 0, 0)
; #define AT_LOADK(t) do { AT_DMA(kg[0] + (size_t)(t) * 65536, ldsl + ((t) & 1) * AT_KS + dw); AT_DMA(kg[1] + (size_t)(t) * 65536, ldsl + ((t) & 1) * AT_KS + dw + 1024); } while (0)
; #define AT_LOADV(t) do { AT_DMA(vg[0] + (t) * 64, ldsl + AT_V0 + ((t) & 1) * AT_KS + dw); AT_DMA(vg[1] + (t) * 64, ldsl + AT_V0 + ((t) & 1) * AT_KS + dw + 1024); } while (0)
; template <bool NEAR>
; DI void attn_qk(f32x16& s0, f32x16& s1, ldsp_t kb, const int* kro, const bf16x8* qf, int dtile, const float* tb2, int hi, int qg, int r32) {
;     ...
;         const int base = dtile * 64 + 8 * hi - (qg & 1) * 32 - r32 + 128;
; #pragma unroll
;         for (int k = 0; k < 16; ++k) { const int i0 = base + (k & 7) + 16 * (k >> 3), i1 = i0 + 32; s0[k] = tb2[i0 < 0 ? 0 : i0]; s1[k] = tb2[i1 < 0 ? 0 : i1]; }
;     }
; #pragma unroll
;     for (int ks = 0; ks < 4; ++ks) { s0 = MFMA32(a[2 * ks], qf[ks], s0); s1 = MFMA32(a[2 * ks + 1], qf[ks], s1); }
; DI void attn_pv(f32x16& s0, f32x16& s1, ldsp_t vb, const int* vro, f32x16* o, float& lsum) {
; #pragma unroll
;     for (int k = 0; k < 16; ++k) { s0[k] = __builtin_amdgcn_exp2f(s0[k]); s1[k] = __builtin_amdgcn_exp2f(s1[k]); }
;     float ps = 0.f;
; #pragma unroll
;     for (int k = 0; k < 16; ++k) ps += s0[k] + s1[k];
;     lsum += ps;
;     bf16x8 pk[4]; pk[0] = pack8(s0, 0); pk[1] = pack8(s0, 1); pk[2] = pack8(s1, 0); pk[3] = pack8(s1, 1);
; #pragma unroll
;     for (int kk = 0; kk < 4; ++kk)
; #pragma unroll
;         for (int et = 0; et < 4; ++et) {
;             const bf16x8 a = *(const __attribute__((address_space(3))) bf16x8*)(vb + vro[kk] + et * 4096);
;             o[et] = MFMA32(a, pk[kk], o[et]);
;         }
; }
; DI void attn_mfma_phase(PP P, int l, unsigned char* lds, int G, int cid) {
;     ...
;         for (; kt < 2 * j; ++kt) {
;             AT_LOADK(kt + 2); AT_LOADV(kt + 1);
;             attn_qk<true>(sn0, sn1, ldsl + ((kt + 1) & 1) * AT_KS, kro, qf, kt + 1 - mychunk, tb2, hi, qg, r32);
;             attn_pv(sc0, sc1, ldsl + (kt & 1) * AT_KS, vro, o, lsum);
;             sc0 = sn0; sc1 = sn1;
;             __syncthreads();
;         }
	v_mfma_f32_32x32x16_bf16 v[16:31], v[6:9], v[132:135], v[16:31]
	ds_read_b128 v[2:5], v250 offset:32768
	v_cvt_pk_bf16_f32 v130, v198, v199
	v_cvt_pk_bf16_f32 v131, v238, v239
	v_add_f32_e32 v198, v198, v199
	s_waitcnt lgkmcnt(1)
	v_mfma_f32_32x32x16_bf16 v[96:111], v[136:139], v[156:159], v[96:111]
	ds_read_b128 v[6:9], v250 offset:36864
	v_add_f32_e32 v238, v238, v239
	v_add_f32_e32 v14, v14, v168
	v_add_f32_e32 v198, v198, v238
	s_waitcnt lgkmcnt(11)
	v_mfma_f32_32x32x16_bf16 v[96:111], v[140:143], v[152:155], v[96:111]
	ds_read_b128 v[136:139], v250 offset:40960
	v_add_f32_e32 v14, v14, v198
	v_add_f32_e32 v189, v189, v14
	s_waitcnt lgkmcnt(8)
	v_mfma_f32_32x32x16_bf16 v[96:111], v[240:243], v[148:151], v[96:111]
	ds_read_b128 v[140:143], v250 offset:45056
	v_exp_f32_e32 v14, v88
	v_exp_f32_e32 v15, v89
	v_exp_f32_e32 v168, v90
	s_waitcnt lgkmcnt(6)
	v_mfma_f32_32x32x16_bf16 v[96:111], v[244:247], v[144:147], v[96:111]
	ds_read_b128 v[240:243], v251 offset:32768
	v_exp_f32_e32 v169, v91
	v_exp_f32_e32 v198, v92
	v_exp_f32_e32 v199, v93
	s_waitcnt lgkmcnt(4)
	v_mfma_f32_32x32x16_bf16 v[64:79], v[2:5], v[128:131], v[64:79]
	ds_read_b128 v[244:247], v251 offset:36864
	v_exp_f32_e32 v238, v94
	v_exp_f32_e32 v239, v95
	v_cvt_pk_bf16_f32 v132, v14, v15
	v_cvt_pk_bf16_f32 v133, v168, v169
	s_waitcnt lgkmcnt(4)
	v_mfma_f32_32x32x16_bf16 v[48:63], v[6:9], v[128:131], v[48:63]
	ds_read_b128 v[2:5], v251 offset:40960
	v_add_f32_e32 v14, v14, v15
	v_add_f32_e32 v168, v168, v169
	v_cvt_pk_bf16_f32 v134, v198, v199
	v_cvt_pk_bf16_f32 v135, v238, v239
	v_add_u32_e32 v112, 0xc0, v0
	v_max_i32_e32 v112, 0xffffffe0, v112
	v_lshl_add_u32 v112, v112, 2, s61
	ds_read_b32 v80, v112 offset:128
	v_add_u32_e32 v113, 0xc1, v0
	v_max_i32_e32 v113, 0xffffffe0, v113
	v_lshl_add_u32 v113, v113, 2, s61
	ds_read_b32 v81, v113 offset:128
	s_waitcnt lgkmcnt(6)
	v_mfma_f32_32x32x16_bf16 v[32:47], v[136:139], v[128:131], v[32:47]
	ds_read_b128 v[6:9], v251 offset:45056
	v_add_f32_e32 v198, v198, v199
	v_add_f32_e32 v238, v238, v239
	v_add_f32_e32 v14, v14, v168
	v_add_u32_e32 v114, 0xc2, v0
	v_max_i32_e32 v114, 0xffffffe0, v114
	v_lshl_add_u32 v114, v114, 2, s61
	ds_read_b32 v82, v114 offset:128
	v_add_u32_e32 v115, 0xc3, v0
	v_max_i32_e32 v115, 0xffffffe0, v115
	v_lshl_add_u32 v115, v115, 2, s61
	ds_read_b32 v83, v115 offset:128
	v_add_u32_e32 v116, 0xc4, v0
	v_max_i32_e32 v116, 0xffffffe0, v116
	v_lshl_add_u32 v116, v116, 2, s61
	ds_read_b32 v84, v116 offset:128
	s_waitcnt lgkmcnt(9)
	v_mfma_f32_32x32x16_bf16 v[16:31], v[140:143], v[128:131], v[16:31]
	ds_read_b128 v[136:139], v252 offset:8192
	v_add_f32_e32 v198, v198, v238
	v_add_f32_e32 v14, v14, v198
	v_add_f32_e32 v189, v189, v14
	v_add_u32_e32 v117, 0xc5, v0
	v_max_i32_e32 v117, 0xffffffe0, v117
	v_lshl_add_u32 v117, v117, 2, s61
	ds_read_b32 v85, v117 offset:128
	v_add_u32_e32 v118, 0xc6, v0
	v_max_i32_e32 v118, 0xffffffe0, v118
	v_lshl_add_u32 v118, v118, 2, s61
	ds_read_b32 v86, v118 offset:128
	v_add_u32_e32 v119, 0xc7, v0
	v_max_i32_e32 v119, 0xffffffe0, v119
	v_lshl_add_u32 v119, v119, 2, s61
	ds_read_b32 v87, v119 offset:128
	s_waitcnt lgkmcnt(12)
	v_mfma_f32_32x32x16_bf16 v[64:79], v[240:243], v[132:135], v[64:79]
	ds_read_b128 v[140:143], v253 offset:8192
	v_exp_f32_e32 v14, v96
	v_exp_f32_e32 v15, v97
	v_exp_f32_e32 v168, v98
	v_add_u32_e32 v120, 0xd0, v0
	v_max_i32_e32 v120, 0xffffffe0, v120
	v_lshl_add_u32 v120, v120, 2, s61
	ds_read_b32 v88, v120 offset:128
	v_add_u32_e32 v121, 0xd1, v0
	v_max_i32_e32 v121, 0xffffffe0, v121
	v_lshl_add_u32 v121, v121, 2, s61
	ds_read_b32 v89, v121 offset:128
	v_add_u32_e32 v122, 0xd2, v0
	v_max_i32_e32 v122, 0xffffffe0, v122
	v_lshl_add_u32 v122, v122, 2, s61
	ds_read_b32 v90, v122 offset:128
	s_waitcnt lgkmcnt(15)
	v_mfma_f32_32x32x16_bf16 v[48:63], v[244:247], v[132:135], v[48:63]
	ds_read_b128 v[240:243], v233 offset:8192
	v_exp_f32_e32 v169, v99
	v_exp_f32_e32 v198, v100
	v_exp_f32_e32 v199, v101
	v_add_u32_e32 v123, 0xd3, v0
	v_max_i32_e32 v123, 0xffffffe0, v123
	v_lshl_add_u32 v123, v123, 2, s61
	ds_read_b32 v91, v123 offset:128
	v_add_u32_e32 v124, 0xd4, v0
	v_max_i32_e32 v124, 0xffffffe0, v124
	v_lshl_add_u32 v124, v124, 2, s61
	ds_read_b32 v92, v124 offset:128
	v_add_u32_e32 v125, 0xd5, v0
	v_max_i32_e32 v125, 0xffffffe0, v125
	v_lshl_add_u32 v125, v125, 2, s61
	ds_read_b32 v93, v125 offset:128
	s_waitcnt lgkmcnt(15)
	v_mfma_f32_32x32x16_bf16 v[32:47], v[2:5], v[132:135], v[32:47]
	ds_read_b128 v[244:247], v234 offset:8192
	v_exp_f32_e32 v238, v102
	v_exp_f32_e32 v239, v103
	v_cvt_pk_bf16_f32 v128, v14, v15
	v_add_u32_e32 v126, 0xd6, v0
	v_max_i32_e32 v126, 0xffffffe0, v126
	v_lshl_add_u32 v126, v126, 2, s61
	ds_read_b32 v94, v126 offset:128
	v_add_u32_e32 v127, 0xd7, v0
	v_max_i32_e32 v127, 0xffffffe0, v127
	v_lshl_add_u32 v127, v127, 2, s61
	ds_read_b32 v95, v127 offset:128
	s_waitcnt lgkmcnt(15)
	v_mfma_f32_32x32x16_bf16 v[16:31], v[6:9], v[132:135], v[16:31]
	v_cvt_pk_bf16_f32 v129, v168, v169
	v_cvt_pk_bf16_f32 v130, v198, v199
	v_cvt_pk_bf16_f32 v131, v238, v239
	s_waitcnt lgkmcnt(0)
	v_mfma_f32_32x32x16_bf16 v[80:95], v[136:139], v[156:159], v[80:95]
	v_add_f32_e32 v14, v14, v15
	v_add_f32_e32 v168, v168, v169
	v_add_f32_e32 v198, v198, v199
	v_add_f32_e32 v238, v238, v239
	v_mfma_f32_32x32x16_bf16 v[80:95], v[140:143], v[152:155], v[80:95]
	v_add_f32_e32 v14, v14, v168
	v_add_f32_e32 v198, v198, v238
	v_add_f32_e32 v235, v14, v198
	s_waitcnt vmcnt(8) lgkmcnt(0)
	s_barrier
	v_mfma_f32_32x32x16_bf16 v[80:95], v[240:243], v[148:151], v[80:95]
	v_lshl_add_u64 v[12:13], v[12:13], 0, s[34:35]
	v_lshl_add_u64 v[10:11], v[10:11], 0, s[34:35]
	v_add_u32_e32 v232, 64, v232
	s_add_i32 s4, s4, 64
	s_add_i32 s38, s38, 1
	s_cmp_lt_i32 s38, s13
	v_mfma_f32_32x32x16_bf16 v[80:95], v[244:247], v[144:147], v[80:95]
	s_cbranch_scc1 .LBB0_217
	s_nop 11
	v_mov_b64_e32 v[142:143], v[94:95]
	v_mov_b64_e32 v[126:127], v[110:111]
	v_mov_b64_e32 v[140:141], v[92:93]
	v_mov_b64_e32 v[138:139], v[90:91]
	v_mov_b64_e32 v[136:137], v[88:89]
	v_mov_b64_e32 v[134:135], v[86:87]
	v_mov_b64_e32 v[132:133], v[84:85]
	v_mov_b64_e32 v[130:131], v[82:83]
	v_mov_b64_e32 v[128:129], v[80:81]
	v_mov_b64_e32 v[124:125], v[108:109]
	v_mov_b64_e32 v[122:123], v[106:107]
	v_mov_b64_e32 v[120:121], v[104:105]
	v_mov_b64_e32 v[118:119], v[102:103]
	v_mov_b64_e32 v[116:117], v[100:101]
	v_mov_b64_e32 v[114:115], v[98:99]
	v_mov_b64_e32 v[112:113], v[96:97]
